# v028 plus GEMM prologues issue both staging batches (14 LDS-DMA loads) before the first wait
# baseline (speedup 1.0000x reference)
; #define PG8_STAGE(bufoff, gbase, voff) do { _Pragma("unroll") for (int _i = 0; _i < 2; ++_i) \
;         __builtin_amdgcn_global_load_lds((const unsigned*)((const char*)(gbase) + (voff)[_i]), (LAS unsigned*)(lds + (bufoff) + ldsw + _i * 8192), 16, 0, 0); } while (0)
; #define PG8_WAIT_V(n) asm volatile("s_waitcnt vmcnt(" #n ")" ::: "memory")
; #define PG8_BAR __builtin_amdgcn_s_barrier()
; template <class Epi, bool ALIGN_EPI, bool SP2, bool ROWHALF = false>
; DI void gemm_phase(LAS unsigned char* lds, const Gemm g, const StaticOrder& S, const Epi& E) {
;     ...
;     for (int i = 0; i < 2; ++i) { int R, C; stage_rc(tid * 16 + i * 8192, R, C); const int Rb = Epi::PERM ? ((R & ~31) + perm32(R & 31)) : R;
;         voffA[i] = (unsigned)(R * g.lda + C) * 2u; voffB[i] = (unsigned)(Rb * g.ldb + C) * 2u; }
;     const size_t kstep = (size_t)(BK * 2);
;     const size_t hstepA = (size_t)HALF * g.lda * 2, hstepB = (size_t)HALF * g.ldb * 2;
;     const size_t tstepA = 2 * hstepA, tstepB = 2 * hstepB;
;     const size_t hA0 = (ROWHALF && g.rowswap) ? hstepA : 0, hA1 = (ROWHALF && g.rowswap) ? 0 : hstepA;
;     const unsigned ldsw = (unsigned)wid * 1024u;
;     const int aoff = lds_byte(wr * 64 + fr, fq * 8), boff = lds_byte(wc * 32 + fr, fq * 8);
;     ...
;     if constexpr (SP2) {
;         PG8_STAGE(PG8_SB(0, 0), cB, voffB); PG8_STAGE(PG8_SB(0, 1), cB + hstepB, voffB); PG8_STAGE(PG8_SA(0, 0), cA + hA0, voffA); PG8_STAGE(PG8_SA(0, 1), cA + hA1, voffA);
;         if (wr == 1) PG8_BAR;
;         PG8_WAIT_V(2); PG8_BAR;
;         PG8_STAGE(PG8_SB(1, 0), cB + kstep, voffB); PG8_STAGE(PG8_SA(1, 0), cA + hA0 + kstep, voffA); PG8_STAGE(PG8_SB(1, 1), cB + hstepB + kstep, voffB);
;         PG8_WAIT_V(6); PG8_BAR;
.LBB0_111:
	v_lshrrev_b32_e32 v20, 1, v6
	v_and_b32_e32 v20, 24, v20
	v_mov_b32_e32 v135, v97
	v_and_b32_e32 v7, 15, v6
	v_lshlrev_b32_e32 v21, 1, v20
	v_lshlrev_b32_e32 v6, 2, v6
	v_lshl_add_u64 v[12:13], s[0:1], 0, v[96:97]
	v_lshl_add_u64 v[14:15], s[0:1], 0, v[134:135]
	v_lshl_or_b32 v146, s21, 6, v7
	v_lshl_or_b32 v7, v7, 6, v21
	s_lshl_b32 s0, s21, 13
	v_and_b32_e32 v6, 32, v6
	v_bitop3_b32 v21, v7, s0, v6 bitop3:0xde
	s_lshl_b32 s0, s11, 5
	s_and_b32 s0, s0, 0x60
	v_lshl_add_u64 v[8:9], s[78:79], 0, v[96:97]
	s_lshl_b32 s1, s0, 7
	v_lshl_add_u64 v[10:11], s[78:79], 0, v[134:135]
	v_mov_b32_e32 v139, v97
	v_bitop3_b32 v147, v7, s1, v6 bitop3:0xde
	s_add_i32 m0, s7, 0x18000
	v_lshl_add_u64 v[6:7], v[8:9], 0, s[38:39]
	v_lshl_add_u64 v[16:17], s[76:77], 0, v[138:139]
	v_mov_b32_e32 v137, v97
	global_load_lds_dwordx4 v[6:7], off
	v_lshl_add_u64 v[6:7], v[10:11], 0, s[38:39]
	s_add_i32 m0, s7, 0x1a000
	s_add_i32 s26, s7, 0x8000
	v_lshl_add_u64 v[18:19], s[76:77], 0, v[136:137]
	global_load_lds_dwordx4 v[6:7], off
	v_lshl_add_u64 v[6:7], v[16:17], 0, s[38:39]
	s_mov_b32 m0, s26
	s_add_i32 s27, s7, 0xa000
	global_load_lds_dwordx4 v[6:7], off
	v_lshl_add_u64 v[6:7], v[18:19], 0, s[38:39]
	s_mov_b32 m0, s27
	s_lshl_b32 s11, s97, 8
	global_load_lds_dwordx4 v[6:7], off
	s_add_i32 m0, s7, 0x1c000
	v_lshl_add_u64 v[6:7], v[12:13], 0, s[38:39]
	global_load_lds_dwordx4 v[6:7], off
	v_lshl_add_u64 v[6:7], v[14:15], 0, s[38:39]
	s_add_i32 m0, s7, 0x1e000
	v_add_u32_e32 v3, v5, v3
	global_load_lds_dwordx4 v[6:7], off
	s_waitcnt vmcnt(8)
	s_barrier
	s_waitcnt vmcnt(6)
	v_add_u32_e32 v0, v2, v0
	s_cmpk_lt_u32 s20, 0x100
	v_add_lshl_u32 v4, v3, v4, 1
	v_mov_b32_e32 v5, v97
	v_add_lshl_u32 v0, v0, v1, 1
	v_mov_b32_e32 v1, v97
	s_mov_b32 s43, s72
	s_cselect_b64 s[52:53], -1, 0
	v_or_b32_e32 v148, s0, v20
	v_lshl_add_u64 v[140:141], s[18:19], 0, v[4:5]
	v_lshl_add_u64 v[142:143], s[18:19], 0, v[0:1]
	s_mov_b32 s46, 0
	v_add_u32_e32 v149, 0, v21
	s_barrier
	s_branch .LBB0_114

; #define PG8_STAGE(bufoff, gbase, voff) do { _Pragma("unroll") for (int _i = 0; _i < 2; ++_i) \
;         __builtin_amdgcn_global_load_lds((const unsigned*)((const char*)(gbase) + (voff)[_i]), (LAS unsigned*)(lds + (bufoff) + ldsw + _i * 8192), 16, 0, 0); } while (0)
; #define PG8_WAIT_V(n) asm volatile("s_waitcnt vmcnt(" #n ")" ::: "memory")
; #define PG8_BAR __builtin_amdgcn_s_barrier()
; template <class Epi, bool ALIGN_EPI, bool SP2, bool ROWHALF = false>
; DI void gemm_phase(LAS unsigned char* lds, const Gemm g, const StaticOrder& S, const Epi& E) {
;     ...
;     f32x4 acc[2][2][4][2];
; #pragma unroll
;     for (int a = 0; a < 2; ++a)
; #pragma unroll
;         for (int b = 0; b < 2; ++b)
; #pragma unroll
;             for (int m = 0; m < 4; ++m)
; #pragma unroll
;                 for (int n = 0; n < 2; ++n) acc[a][b][m][n] = (f32x4){0.f, 0.f, 0.f, 0.f};
;     ...
;     if constexpr (SP2) {
;         PG8_STAGE(PG8_SB(0, 0), cB, voffB); PG8_STAGE(PG8_SB(0, 1), cB + hstepB, voffB); PG8_STAGE(PG8_SA(0, 0), cA + hA0, voffA); PG8_STAGE(PG8_SA(0, 1), cA + hA1, voffA);
;         if (wr == 1) PG8_BAR;
;         PG8_WAIT_V(2); PG8_BAR;
;         PG8_STAGE(PG8_SB(1, 0), cB + kstep, voffB); PG8_STAGE(PG8_SA(1, 0), cA + hA0 + kstep, voffA); PG8_STAGE(PG8_SB(1, 1), cB + hstepB + kstep, voffB);
;         PG8_WAIT_V(6); PG8_BAR;
.LBB0_151:
	v_mov_b32_e32 v137, v97
	v_lshl_add_u64 v[6:7], s[50:51], 0, v[136:137]
	v_mov_b32_e32 v109, v97
	v_lshl_add_u64 v[8:9], s[50:51], 0, v[108:109]
	v_mov_b32_e32 v139, v97
	s_add_i32 m0, s7, 0x18000
	v_lshl_add_u64 v[6:7], v[6:7], 0, s[38:39]
	v_lshl_add_u64 v[14:15], s[52:53], 0, v[138:139]
	v_mov_b32_e32 v135, v97
	global_load_lds_dwordx4 v[6:7], off
	v_lshl_add_u64 v[6:7], v[8:9], 0, s[38:39]
	s_add_i32 m0, s7, 0x1a000
	s_add_i32 s46, s7, 0x8000
	v_lshl_add_u64 v[16:17], s[52:53], 0, v[134:135]
	global_load_lds_dwordx4 v[6:7], off
	v_lshl_add_u64 v[6:7], v[14:15], 0, s[38:39]
	s_mov_b32 m0, s46
	s_add_i32 s47, s7, 0xa000
	v_lshl_add_u64 v[10:11], s[0:1], 0, v[136:137]
	global_load_lds_dwordx4 v[6:7], off
	v_lshl_add_u64 v[6:7], v[16:17], 0, s[38:39]
	s_mov_b32 m0, s47
	v_lshl_add_u64 v[12:13], s[0:1], 0, v[108:109]
	global_load_lds_dwordx4 v[6:7], off
	s_add_i32 m0, s7, 0x1c000
	v_lshl_add_u64 v[6:7], v[10:11], 0, s[38:39]
	global_load_lds_dwordx4 v[6:7], off
	v_lshl_add_u64 v[6:7], v[12:13], 0, s[38:39]
	s_add_i32 m0, s7, 0x1e000
	v_add_u32_e32 v3, v5, v3
	global_load_lds_dwordx4 v[6:7], off
	s_waitcnt vmcnt(8)
	s_barrier
	v_and_b32_e32 v145, 15, v144
	v_and_b32_e32 v6, 48, v144
	v_lshlrev_b32_e32 v7, 2, v144
	v_add_lshl_u32 v96, v3, v4, 1
	v_add_u32_e32 v0, v2, v0
	s_and_b32 s45, s27, 3
	s_lshl_b32 s0, s20, 13
	v_lshl_or_b32 v6, v145, 6, v6
	v_and_b32_e32 v7, 32, v7
	v_lshl_add_u64 v[140:141], s[18:19], 0, v[96:97]
	v_add_lshl_u32 v96, v0, v1, 1
	v_bitop3_b32 v8, v6, s0, v7 bitop3:0xde
	s_lshl_b32 s0, s45, 12
	s_waitcnt vmcnt(6)
	v_lshl_add_u64 v[142:143], s[18:19], 0, v[96:97]
	v_mov_b32_e32 v96, v97
	v_mov_b32_e32 v98, v97
	v_mov_b32_e32 v99, v97
	s_lshl_b32 s11, s20, 6
	v_bitop3_b32 v146, v6, s0, v7 bitop3:0xde
	v_add_u32_e32 v147, 0, v8
	v_mov_b64_e32 v[132:133], v[98:99]
	v_mov_b64_e32 v[102:103], v[98:99]
	v_mov_b64_e32 v[124:125], v[98:99]
	v_mov_b64_e32 v[128:129], v[98:99]
	v_mov_b64_e32 v[88:89], v[96:97]
	v_mov_b64_e32 v[92:93], v[96:97]
	v_mov_b64_e32 v[72:73], v[96:97]
	v_mov_b64_e32 v[76:77], v[96:97]
	v_mov_b64_e32 v[112:113], v[98:99]
	v_mov_b64_e32 v[120:121], v[98:99]
	v_mov_b64_e32 v[106:107], v[98:99]
	v_mov_b64_e32 v[116:117], v[98:99]
	v_mov_b64_e32 v[80:81], v[96:97]
	v_mov_b64_e32 v[84:85], v[96:97]
	v_mov_b64_e32 v[64:65], v[96:97]
	v_mov_b64_e32 v[68:69], v[96:97]
	v_mov_b64_e32 v[56:57], v[96:97]
	v_mov_b64_e32 v[60:61], v[96:97]
	v_mov_b64_e32 v[40:41], v[96:97]
	v_mov_b64_e32 v[44:45], v[96:97]
	v_mov_b64_e32 v[24:25], v[96:97]
	v_mov_b64_e32 v[28:29], v[96:97]
	v_mov_b64_e32 v[8:9], v[96:97]
	v_mov_b64_e32 v[12:13], v[96:97]
	v_mov_b64_e32 v[48:49], v[96:97]
	v_mov_b64_e32 v[52:53], v[96:97]
	v_mov_b64_e32 v[32:33], v[96:97]
	v_mov_b64_e32 v[36:37], v[96:97]
	v_mov_b64_e32 v[16:17], v[96:97]
	v_mov_b64_e32 v[20:21], v[96:97]
	v_mov_b64_e32 v[0:1], v[96:97]
	v_mov_b64_e32 v[4:5], v[96:97]
	v_readlane_b32 s86, v255, 21
	v_or_b32_e32 v216, s11, v145
	s_mov_b32 s49, s72
	s_mov_b32 s19, 0
	v_mov_b64_e32 v[130:131], v[96:97]
	v_mov_b64_e32 v[100:101], v[96:97]
	v_mov_b64_e32 v[122:123], v[96:97]
	v_mov_b64_e32 v[126:127], v[96:97]
	v_mov_b64_e32 v[90:91], v[98:99]
	v_mov_b64_e32 v[94:95], v[98:99]
	v_mov_b64_e32 v[74:75], v[98:99]
	v_mov_b64_e32 v[78:79], v[98:99]
	v_mov_b64_e32 v[110:111], v[96:97]
	v_mov_b64_e32 v[118:119], v[96:97]
	v_mov_b64_e32 v[104:105], v[96:97]
	v_mov_b64_e32 v[114:115], v[96:97]
	v_mov_b64_e32 v[82:83], v[98:99]
	v_mov_b64_e32 v[86:87], v[98:99]
	v_mov_b64_e32 v[66:67], v[98:99]
	v_mov_b64_e32 v[70:71], v[98:99]
	v_mov_b64_e32 v[58:59], v[98:99]
	v_mov_b64_e32 v[62:63], v[98:99]
	v_mov_b64_e32 v[42:43], v[98:99]
	v_mov_b64_e32 v[46:47], v[98:99]
	v_mov_b64_e32 v[26:27], v[98:99]
	v_mov_b64_e32 v[30:31], v[98:99]
	v_mov_b64_e32 v[10:11], v[98:99]
	v_mov_b64_e32 v[14:15], v[98:99]
	v_mov_b64_e32 v[50:51], v[98:99]
	v_mov_b64_e32 v[54:55], v[98:99]
	v_mov_b64_e32 v[34:35], v[98:99]
	v_mov_b64_e32 v[38:39], v[98:99]
	v_mov_b64_e32 v[18:19], v[98:99]
	v_mov_b64_e32 v[22:23], v[98:99]
	v_mov_b64_e32 v[2:3], v[98:99]
	v_mov_b64_e32 v[6:7], v[98:99]
	v_readlane_b32 s87, v255, 22
	s_barrier
	s_branch .LBB0_153

; #define PG8_STAGE(bufoff, gbase, voff) do { _Pragma("unroll") for (int _i = 0; _i < 2; ++_i) \
;         __builtin_amdgcn_global_load_lds((const unsigned*)((const char*)(gbase) + (voff)[_i]), (LAS unsigned*)(lds + (bufoff) + ldsw + _i * 8192), 16, 0, 0); } while (0)
; #define PG8_WAIT_V(n) asm volatile("s_waitcnt vmcnt(" #n ")" ::: "memory")
; #define PG8_BAR __builtin_amdgcn_s_barrier()
; template <class Epi, bool ALIGN_EPI, bool SP2, bool ROWHALF = false>
; DI void gemm_phase(LAS unsigned char* lds, const Gemm g, const StaticOrder& S, const Epi& E) {
;     ...
;     for (int i = 0; i < 2; ++i) { int R, C; stage_rc(tid * 16 + i * 8192, R, C); const int Rb = Epi::PERM ? ((R & ~31) + perm32(R & 31)) : R;
;         voffA[i] = (unsigned)(R * g.lda + C) * 2u; voffB[i] = (unsigned)(Rb * g.ldb + C) * 2u; }
;     const size_t kstep = (size_t)(BK * 2);
;     const size_t hstepA = (size_t)HALF * g.lda * 2, hstepB = (size_t)HALF * g.ldb * 2;
;     const size_t tstepA = 2 * hstepA, tstepB = 2 * hstepB;
;     const size_t hA0 = (ROWHALF && g.rowswap) ? hstepA : 0, hA1 = (ROWHALF && g.rowswap) ? 0 : hstepA;
;     const unsigned ldsw = (unsigned)wid * 1024u;
;     const int aoff = lds_byte(wr * 64 + fr, fq * 8), boff = lds_byte(wc * 32 + fr, fq * 8);
;     ...
;     if constexpr (SP2) {
;         PG8_STAGE(PG8_SB(0, 0), cB, voffB); PG8_STAGE(PG8_SB(0, 1), cB + hstepB, voffB); PG8_STAGE(PG8_SA(0, 0), cA + hA0, voffA); PG8_STAGE(PG8_SA(0, 1), cA + hA1, voffA);
;         if (wr == 1) PG8_BAR;
;         PG8_WAIT_V(2); PG8_BAR;
;         PG8_STAGE(PG8_SB(1, 0), cB + kstep, voffB); PG8_STAGE(PG8_SA(1, 0), cA + hA0 + kstep, voffA); PG8_STAGE(PG8_SB(1, 1), cB + hstepB + kstep, voffB);
;         PG8_WAIT_V(6); PG8_BAR;
.LBB0_234:
	v_lshrrev_b32_e32 v16, 1, v14
	v_and_b32_e32 v16, 24, v16
	v_and_b32_e32 v15, 15, v14
	v_lshlrev_b32_e32 v17, 1, v16
	v_lshlrev_b32_e32 v14, 2, v14
	v_lshl_or_b32 v144, s21, 6, v15
	v_lshl_or_b32 v15, v15, 6, v17
	s_lshl_b32 s21, s21, 13
	v_and_b32_e32 v14, 32, v14
	s_lshl_b32 s13, s13, 5
	v_bitop3_b32 v17, v15, s21, v14 bitop3:0xde
	s_and_b32 s21, s13, 0x60
	s_lshl_b32 s13, s21, 7
	s_and_b64 s[24:25], s[0:1], exec
	v_readlane_b32 s24, v255, 2
	v_readlane_b32 s25, v255, 3
	s_cselect_b32 s26, 0, s25
	s_cselect_b32 s27, 0xf0, s24
	s_add_i32 m0, s9, 0x18000
	v_lshl_add_u64 v[6:7], v[6:7], 0, s[38:39]
	global_load_lds_dwordx4 v[6:7], off
	v_lshl_add_u64 v[4:5], v[4:5], 0, s[38:39]
	s_add_i32 m0, s9, 0x1a000
	s_add_i32 s31, s9, 0x8000
	s_add_i32 s46, s9, 0xa000
	global_load_lds_dwordx4 v[4:5], off
	v_lshl_add_u64 v[0:1], v[0:1], 0, s[38:39]
	s_mov_b32 m0, s31
	s_add_u32 s24, s76, 0x80080
	global_load_lds_dwordx4 v[0:1], off
	v_lshl_add_u64 v[0:1], v[2:3], 0, s[38:39]
	s_mov_b32 m0, s46
	s_addc_u32 s25, s77, 0
	global_load_lds_dwordx4 v[0:1], off
	s_add_i32 m0, s9, 0x1c000
	v_lshl_add_u64 v[0:1], s[24:25], 0, v[96:97]
	global_load_lds_dwordx4 v[0:1], off
	v_lshl_add_u64 v[0:1], s[24:25], 0, v[130:131]
	s_add_i32 m0, s9, 0x1e000
	s_cmpk_lt_u32 s20, 0x100
	global_load_lds_dwordx4 v[0:1], off
	s_waitcnt vmcnt(8)
	s_barrier
	v_lshlrev_b32_e32 v0, 15, v12
	v_and_b32_e32 v0, 0xffff0000, v0
	v_lshl_add_u32 v0, v11, 12, v0
	v_and_b32_e32 v1, 1, v12
	v_lshl_or_b32 v0, v1, 6, v0
	v_lshl_add_u32 v136, v13, 1, v0
	v_lshlrev_b32_e32 v0, 15, v8
	v_and_b32_e32 v0, 0xffff0000, v0
	s_waitcnt vmcnt(6)
	v_lshl_add_u32 v0, v9, 12, v0
	v_and_b32_e32 v1, 1, v8
	v_lshl_or_b32 v0, v1, 6, v0
	v_bitop3_b32 v145, v15, s13, v14 bitop3:0xde
	s_mov_b32 s13, 0
	s_cselect_b64 s[24:25], -1, 0
	v_or_b32_e32 v146, s21, v16
	v_mov_b32_e32 v137, v97
	v_lshl_add_u32 v138, v10, 1, v0
	v_mov_b32_e32 v139, v97
	v_add_u32_e32 v147, 0, v17
	s_barrier
	s_branch .LBB0_237

; #define PG8_STAGE(bufoff, gbase, voff) do { _Pragma("unroll") for (int _i = 0; _i < 2; ++_i) \
;         __builtin_amdgcn_global_load_lds((const unsigned*)((const char*)(gbase) + (voff)[_i]), (LAS unsigned*)(lds + (bufoff) + ldsw + _i * 8192), 16, 0, 0); } while (0)
; #define PG8_WAIT_V(n) asm volatile("s_waitcnt vmcnt(" #n ")" ::: "memory")
; #define PG8_BAR __builtin_amdgcn_s_barrier()
; template <class Epi, bool ALIGN_EPI, bool SP2, bool ROWHALF = false>
; DI void gemm_phase(LAS unsigned char* lds, const Gemm g, const StaticOrder& S, const Epi& E) {
;     ...
;     f32x4 acc[2][2][4][2];
; #pragma unroll
;     for (int a = 0; a < 2; ++a)
; #pragma unroll
;         for (int b = 0; b < 2; ++b)
; #pragma unroll
;             for (int m = 0; m < 4; ++m)
; #pragma unroll
;                 for (int n = 0; n < 2; ++n) acc[a][b][m][n] = (f32x4){0.f, 0.f, 0.f, 0.f};
;     ...
;     if constexpr (SP2) {
;         PG8_STAGE(PG8_SB(0, 0), cB, voffB); PG8_STAGE(PG8_SB(0, 1), cB + hstepB, voffB); PG8_STAGE(PG8_SA(0, 0), cA + hA0, voffA); PG8_STAGE(PG8_SA(0, 1), cA + hA1, voffA);
;         if (wr == 1) PG8_BAR;
;         PG8_WAIT_V(2); PG8_BAR;
;         PG8_STAGE(PG8_SB(1, 0), cB + kstep, voffB); PG8_STAGE(PG8_SA(1, 0), cA + hA0 + kstep, voffA); PG8_STAGE(PG8_SB(1, 1), cB + hstepB + kstep, voffB);
;         PG8_WAIT_V(6); PG8_BAR;
.LBB0_250:
	v_lshrrev_b32_e32 v16, 1, v12
	v_and_b32_e32 v75, 24, v16
	v_and_b32_e32 v15, 15, v12
	v_lshlrev_b32_e32 v16, 1, v75
	v_lshlrev_b32_e32 v12, 2, v12
	v_lshl_or_b32 v74, s19, 6, v15
	v_lshl_or_b32 v15, v15, 6, v16
	s_lshl_b32 s19, s19, 13
	v_and_b32_e32 v12, 32, v12
	v_bitop3_b32 v16, v15, s19, v12 bitop3:0xde
	s_lshl_b32 s19, s25, 5
	s_and_b32 s25, s19, 0x60
	s_add_i32 m0, s6, 0x18000
	v_lshl_add_u64 v[0:1], v[0:1], 0, s[38:39]
	s_lshl_b32 s19, s25, 7
	global_load_lds_dwordx4 v[0:1], off
	v_lshl_add_u64 v[0:1], v[2:3], 0, s[38:39]
	s_add_i32 m0, s6, 0x1a000
	s_add_i32 s26, s6, 0x8000
	s_add_i32 s27, s6, 0xa000
	global_load_lds_dwordx4 v[0:1], off
	v_lshl_add_u64 v[0:1], v[4:5], 0, s[38:39]
	s_mov_b32 m0, s26
	s_add_u32 s28, s16, 0x80080
	global_load_lds_dwordx4 v[0:1], off
	v_lshl_add_u64 v[0:1], v[6:7], 0, s[38:39]
	s_mov_b32 m0, s27
	s_addc_u32 s29, s17, 0
	global_load_lds_dwordx4 v[0:1], off
	s_add_i32 m0, s6, 0x1c000
	v_lshl_add_u64 v[0:1], s[28:29], 0, v[96:97]
	global_load_lds_dwordx4 v[0:1], off
	v_lshl_add_u64 v[0:1], s[28:29], 0, v[68:69]
	s_add_i32 m0, s6, 0x1e000
	s_add_i32 s18, s18, s23
	global_load_lds_dwordx4 v[0:1], off
	s_waitcnt vmcnt(8)
	s_barrier
	v_lshlrev_b32_e32 v0, 15, v11
	s_lshl_b32 s23, s18, 20
	v_and_b32_e32 v0, 0xffff0000, v0
	v_bitop3_b32 v76, v15, s19, v12 bitop3:0xde
	s_or_b32 s18, s8, s23
	v_lshl_add_u32 v0, v13, 12, v0
	v_and_b32_e32 v1, 1, v11
	v_readlane_b32 s19, v254, 54
	v_lshl_or_b32 v0, v1, 6, v0
	s_add_u32 s18, s19, s18
	v_readlane_b32 s19, v254, 55
	v_lshl_add_u32 v0, v14, 1, v0
	v_mov_b32_e32 v1, v97
	s_addc_u32 s19, s19, 0
	v_lshl_add_u64 v[70:71], s[18:19], 0, v[0:1]
	v_lshlrev_b32_e32 v0, 15, v8
	v_and_b32_e32 v0, 0xffff0000, v0
	v_lshl_add_u32 v0, v9, 12, v0
	v_and_b32_e32 v1, 1, v8
	s_add_u32 s28, s92, s23
	v_lshl_or_b32 v0, v1, 6, v0
	s_addc_u32 s29, s93, 0
	v_lshl_add_u32 v0, v10, 1, v0
	v_mov_b32_e32 v1, v97
	s_add_u32 s5, s5, s22
	s_waitcnt vmcnt(6)
	v_lshl_add_u64 v[72:73], s[18:19], 0, v[0:1]
	s_addc_u32 s18, s4, 0
	v_readlane_b32 s4, v254, 56
	s_add_u32 s4, s4, s5
	v_readlane_b32 s5, v254, 57
	v_mov_b32_e32 v0, 0
	s_addc_u32 s5, s5, s18
	s_mov_b32 s31, -2
	s_mov_b64 s[18:19], 0
	v_add_u32_e32 v77, 0, v16
	v_mov_b32_e32 v1, v0
	v_mov_b32_e32 v2, v0
	v_mov_b32_e32 v3, v0
	v_mov_b32_e32 v8, v0
	v_mov_b32_e32 v9, v0
	v_mov_b32_e32 v10, v0
	v_mov_b32_e32 v11, v0
	v_mov_b32_e32 v16, v0
	v_mov_b32_e32 v17, v0
	v_mov_b32_e32 v18, v0
	v_mov_b32_e32 v19, v0
	v_mov_b32_e32 v24, v0
	v_mov_b32_e32 v25, v0
	v_mov_b32_e32 v26, v0
	v_mov_b32_e32 v27, v0
	v_mov_b32_e32 v32, v0
	v_mov_b32_e32 v33, v0
	v_mov_b32_e32 v34, v0
	v_mov_b32_e32 v35, v0
	v_mov_b32_e32 v40, v0
	v_mov_b32_e32 v41, v0
	v_mov_b32_e32 v42, v0
	v_mov_b32_e32 v43, v0
	v_mov_b32_e32 v48, v0
	v_mov_b32_e32 v49, v0
	v_mov_b32_e32 v50, v0
	v_mov_b32_e32 v51, v0
	v_mov_b32_e32 v56, v0
	v_mov_b32_e32 v57, v0
	v_mov_b32_e32 v58, v0
	v_mov_b32_e32 v59, v0
	v_mov_b32_e32 v4, v0
	v_mov_b32_e32 v5, v0
	v_mov_b32_e32 v6, v0
	v_mov_b32_e32 v7, v0
	v_mov_b32_e32 v12, v0
	v_mov_b32_e32 v13, v0
	v_mov_b32_e32 v14, v0
	v_mov_b32_e32 v15, v0
	v_mov_b32_e32 v20, v0
	v_mov_b32_e32 v21, v0
	v_mov_b32_e32 v22, v0
	v_mov_b32_e32 v23, v0
	v_mov_b32_e32 v28, v0
	v_mov_b32_e32 v29, v0
	v_mov_b32_e32 v30, v0
	v_mov_b32_e32 v31, v0
	v_mov_b32_e32 v36, v0
	v_mov_b32_e32 v37, v0
	v_mov_b32_e32 v38, v0
	v_mov_b32_e32 v39, v0
	v_mov_b32_e32 v44, v0
	v_mov_b32_e32 v45, v0
	v_mov_b32_e32 v46, v0
	v_mov_b32_e32 v47, v0
	v_mov_b32_e32 v52, v0
	v_mov_b32_e32 v53, v0
	v_mov_b32_e32 v54, v0
	v_mov_b32_e32 v55, v0
	v_mov_b32_e32 v60, v0
	v_mov_b32_e32 v61, v0
	v_mov_b32_e32 v62, v0
	v_mov_b32_e32 v63, v0
	s_barrier
	s_waitcnt vmcnt(0)
